# speedup vs baseline: 1.0188x; 1.0053x over previous
; #define p getp()
; __device__ __forceinline__ void pv8(f32x16* o, f32x16& lacc, const char* Vs, i32x8 pf, int r32, int hi) {
;     ...
;   const int one4 = 0x38383838;
;   lacc = mfma8(pf, i32x8{one4, one4, one4, one4, one4, one4, one4, one4}, lacc);
; __device__ __forceinline__ void phase_mla_attn(KP p, char* smem, int wv) {
;   const bf16* Q = (const bf16*)(P_big + OFF_Q); const unsigned char* K8 = (const unsigned char*)(P_big + OFF_K); const unsigned char* Vt8 = (const unsigned char*)(P_big + OFF_V);
;   for (int w = blockIdx.x; w < NSEQ * 1024; w += gridDim.x) {
;     const int s = w >> 10, it = (w >> 8) & 3, b = w & 255, xcd = b & 7, l = b >> 3;
;     const int h = it * 4 + (xcd >> 1), qb = (xcd & 1) * 32 + l;
;     const long t0 = (long)s * SEQ;
;     attn_body8(Q + (t0 + qb * 256) * NUQ + h * 192, K8 + t0 * NUQ + h * 192, Vt8 + ((long)s * 16 + h) * 256 * 8192,
;                P_H + (t0 + qb * 256) * DM + (long)(2 * h) * 16384, SEQ / KVBLK, smem, P_ropeC, P_ropeS, qb * 256, wv);
.LBB0_887:
	s_or_b64 exec, exec, s[8:9]
	s_mov_b64 s[8:9], s[90:91]
	s_and_b64 vcc, exec, s[6:7]
	s_barrier
	s_cbranch_vccnz .LBB0_934
	s_load_dwordx2 s[30:31], s[8:9], 0xa8
	s_movk_i32 s0, 0x1800
	s_mov_b32 s35, 0
	s_movk_i32 s1, 0xffe0
	v_mov_b32_e32 v145, 0
	s_waitcnt lgkmcnt(0)
	s_add_u32 s3, s30, 0x17a40000
	s_addc_u32 s48, s31, 0
	s_add_u32 s49, s30, 0x2be40000
	s_addc_u32 s50, s31, 0
	s_add_u32 s51, s30, 0x25e40000
	s_addc_u32 s52, s31, 0
	s_add_u32 s53, s30, 0xba40000
	s_addc_u32 s54, s31, 0
	s_add_u32 s36, s30, 0xb640000
	s_addc_u32 s37, s31, 0
	s_add_u32 s38, s30, 0xb840000
	s_addc_u32 s39, s31, 0
	s_mov_b32 s55, 0x2aaaaaab
	s_movk_i32 s56, 0xc00
	s_movk_i32 s57, 0x100
	s_movk_i32 s58, 0xd0
	s_movk_i32 s59, 0x50
	s_add_i32 s60, 0, 0x19800
	v_mov_b32_e32 v193, 0x7f7f7f7f
	s_mov_b32 s61, 0x41b8aa3b
	s_mov_b64 s[40:41], 0x60000
	s_mov_b64 s[42:43], 0x4000
	s_mov_b32 s62, 0x8000
	v_mov_b32_e32 v208, 0xf149f2ca
	v_lshrrev_b32_e32 v112, 4, v192
	v_xor_b32_e32 v112, v112, v192
	v_and_b32_e32 v112, 1, v112
	v_cmp_eq_u32_e32 vcc, 0, v112
	v_mov_b32_e32 v112, 0x38383838
	s_nop 1
	v_cndmask_b32_e32 v112, 0, v112, vcc
	v_mov_b32_e32 v244, v112
	v_mov_b32_e32 v245, v112
	v_mov_b32_e32 v246, v112
	v_mov_b32_e32 v247, v112
	v_mov_b32_e32 v248, v112
	v_mov_b32_e32 v249, v112
	v_mov_b32_e32 v250, v112
	v_mov_b32_e32 v251, v112
	s_mov_b32 s63, s89
	s_branch .LBB0_891

; #define SBAR() __builtin_amdgcn_sched_barrier(0)
; __device__ __forceinline__ unsigned short f2bf(float x) { return (unsigned short)(cvtpk(x, x) & 0xffffu); }
; __device__ __forceinline__ void finishSM8(f32x16& p0, f32x16& p1, i32x8& pf) {
; #pragma unroll
;   for (int w = 0; w < 4; ++w) { pf[w] = (int)pk4u8(p0[4 * w], p0[4 * w + 1], p0[4 * w + 2], p0[4 * w + 3]);
;                                 pf[4 + w] = (int)pk4u8(p1[4 * w], p1[4 * w + 1], p1[4 * w + 2], p1[4 * w + 3]); }
; }
; __device__ __forceinline__ void attn_body8(const bf16* __restrict__ Qb, const unsigned char* __restrict__ Kg, const unsigned char* __restrict__ Vg, ...
;     ...
;   finishSM8(pB0, pB1, pf); SBAR();
;   pv8(o, lacc, V_lds + v5 * SHM_V8, pf, r32, hi);
;     ...
;   unsigned short* Ow = reinterpret_cast<unsigned short*>(Ob) + (wid * QBLK + 4 * hi) * 64 + r32;
; #pragma unroll
;   for (int r = 0; r < 16; ++r) { const int orow = (r & 3) + 8 * (r >> 2); const float rl = __builtin_amdgcn_rcpf(lacc[r]);
; #pragma unroll
;     for (int d0 = 0; d0 < 4; ++d0) Ow[orow * 64 + (d0 >> 1) * 16384 + (d0 & 1) * 32] = f2bf(o[d0][r] * rl);
;     SBAR(); }
.LBB0_890:
	v_cndmask_b32_e64 v113, v120, v216, s[6:7]
	v_sub_f32_e32 v113, 0x42c04d6a, v113
	v_add_f32_e32 v80, v80, v113
	v_add_f32_e32 v81, v81, v113
	v_cvt_pk_u8_f32 v80, v80, 0, 0
	v_add_f32_e32 v82, v82, v113
	v_cvt_pk_u8_f32 v80, v81, 1, v80
	v_add_f32_e32 v96, v96, v113
	v_add_f32_e32 v83, v83, v113
	v_cvt_pk_u8_f32 v80, v82, 2, v80
	v_add_f32_e32 v97, v97, v113
	v_add_f32_e32 v114, v89, v113
	v_add_f32_e32 v89, v84, v113
	v_cvt_pk_u8_f32 v84, v83, 3, v80
	v_cvt_pk_u8_f32 v80, v96, 0, 0
	v_add_f32_e32 v98, v98, v113
	v_cvt_pk_u8_f32 v80, v97, 1, v80
	v_add_f32_e32 v99, v99, v113
	v_cvt_pk_u8_f32 v80, v98, 2, v80
	v_add_f32_e32 v115, v88, v113
	v_add_f32_e32 v85, v85, v113
	v_cvt_pk_u8_f32 v88, v99, 3, v80
	v_cvt_pk_u8_f32 v80, v89, 0, 0
	v_add_f32_e32 v86, v86, v113
	v_cvt_pk_u8_f32 v80, v85, 1, v80
	v_add_f32_e32 v100, v100, v113
	v_add_f32_e32 v87, v87, v113
	v_cvt_pk_u8_f32 v80, v86, 2, v80
	v_add_f32_e32 v101, v101, v113
	v_cvt_pk_u8_f32 v85, v87, 3, v80
	v_cvt_pk_u8_f32 v80, v100, 0, 0
	v_add_f32_e32 v102, v102, v113
	v_cvt_pk_u8_f32 v80, v101, 1, v80
	v_add_f32_e32 v103, v103, v113
	v_cvt_pk_u8_f32 v80, v102, 2, v80
	v_cvt_pk_u8_f32 v89, v103, 3, v80
	v_cvt_pk_u8_f32 v80, v115, 0, 0
	v_add_f32_e32 v90, v90, v113
	v_cvt_pk_u8_f32 v80, v114, 1, v80
	v_add_f32_e32 v104, v104, v113
	v_add_f32_e32 v91, v91, v113
	v_cvt_pk_u8_f32 v80, v90, 2, v80
	v_add_f32_e32 v105, v105, v113
	v_cvt_pk_u8_f32 v86, v91, 3, v80
	v_cvt_pk_u8_f32 v80, v104, 0, 0
	v_add_f32_e32 v106, v106, v113
	v_cvt_pk_u8_f32 v80, v105, 1, v80
	v_add_f32_e32 v107, v107, v113
	v_add_f32_e32 v92, v92, v113
	v_cvt_pk_u8_f32 v80, v106, 2, v80
	v_add_f32_e32 v93, v93, v113
	v_cvt_pk_u8_f32 v90, v107, 3, v80
	v_cvt_pk_u8_f32 v80, v92, 0, 0
	v_add_f32_e32 v94, v94, v113
	v_cvt_pk_u8_f32 v80, v93, 1, v80
	s_lshl_b64 s[8:9], s[44:45], 12
	v_add_f32_e32 v108, v108, v113
	v_add_f32_e32 v95, v95, v113
	v_cvt_pk_u8_f32 v80, v94, 2, v80
	s_add_u32 s2, s53, s8
	v_add_f32_e32 v109, v109, v113
	v_cvt_pk_u8_f32 v87, v95, 3, v80
	v_cvt_pk_u8_f32 v80, v108, 0, 0
	s_addc_u32 s9, s54, s9
	s_lshl_b32 s8, s64, 16
	v_add_f32_e32 v110, v110, v113
	v_cvt_pk_u8_f32 v80, v109, 1, v80
	s_add_u32 s8, s2, s8
	v_add_f32_e32 v111, v111, v113
	v_cvt_pk_u8_f32 v80, v110, 2, v80
	s_addc_u32 s9, s9, 0
	v_cvt_pk_u8_f32 v91, v111, 3, v80
	s_add_i32 s2, s12, 0
	v_add3_u32 v80, s2, v146, v144
	ds_read_b128 v[92:95], v80
	ds_read_b128 v[96:99], v80 offset:16
	s_waitcnt lgkmcnt(0)
	v_mfma_scale_f32_32x32x64_f8f6f4 v[48:63], v[84:91], v[92:99], v[48:63], v193, v193 op_sel_hi:[0,0,0]
	ds_read_b128 v[92:95], v80 offset:2560
	ds_read_b128 v[96:99], v80 offset:2576
	v_lshlrev_b32_e32 v144, 1, v209
	s_waitcnt lgkmcnt(0)
	v_mfma_scale_f32_32x32x64_f8f6f4 v[32:47], v[84:91], v[92:99], v[32:47], v193, v193 op_sel_hi:[0,0,0]
	ds_read_b128 v[92:95], v80 offset:5120
	ds_read_b128 v[96:99], v80 offset:5136
	ds_read_b128 v[100:103], v80 offset:7680
	ds_read_b128 v[104:107], v80 offset:7696
	v_lshlrev_b32_e32 v80, 6, v211
	v_lshl_or_b32 v80, v210, 8, v80
	v_ashrrev_i32_e32 v81, 31, v80
	v_lshl_add_u64 v[80:81], v[80:81], 1, s[8:9]
	v_lshl_add_u64 v[80:81], v[80:81], 0, v[144:145]
	v_add_co_u32_e32 v82, vcc, s62, v80
	s_nop 1
	v_addc_co_u32_e32 v83, vcc, 0, v81, vcc
	v_mfma_scale_f32_16x16x128_f8f6f4 v[64:67], v[84:91], v[244:251], v[64:67], v193, v193 op_sel_hi:[0,0,0]
	s_waitcnt lgkmcnt(2)
	v_mfma_scale_f32_32x32x64_f8f6f4 v[16:31], v[84:91], v[92:99], v[16:31], v193, v193 op_sel_hi:[0,0,0]
	s_nop 15
	s_nop 1
	ds_write_b128 v242, v[64:67]
	v_add_u32_e32 v243, v159, v213
	s_waitcnt lgkmcnt(0)
	ds_read_b128 v[64:67], v243
	ds_read_b128 v[68:71], v243 offset:32
	ds_read_b128 v[72:75], v243 offset:64
	ds_read_b128 v[76:79], v243 offset:96
	s_waitcnt lgkmcnt(0)
	v_rcp_f32_e32 v64, v64
	s_nop 0
	v_mul_f32_e32 v48, v48, v64
	v_mul_f32_e32 v32, v32, v64
	v_cvt_pk_bf16_f32 v48, v48, v48
	global_store_short v[80:81], v48, off
	v_cvt_pk_bf16_f32 v32, v32, v32
	global_store_short v[80:81], v32, off offset:64
	v_mul_f32_e32 v16, v16, v64
	s_waitcnt lgkmcnt(0)
	v_mfma_scale_f32_32x32x64_f8f6f4 v[0:15], v[84:91], v[100:107], v[0:15], v193, v193 op_sel_hi:[0,0,0]
	v_cvt_pk_bf16_f32 v16, v16, v16
	global_store_short v[82:83], v16, off
	s_nop 15
	s_nop 2
	v_mul_f32_e32 v0, v0, v64
	v_cvt_pk_bf16_f32 v0, v0, v0
	global_store_short v[82:83], v0, off offset:64
	v_rcp_f32_e32 v0, v65
	s_nop 0
	v_mul_f32_e32 v16, v49, v0
	v_cvt_pk_bf16_f32 v16, v16, v16
	v_mul_f32_e32 v32, v33, v0
	v_mul_f32_e32 v17, v17, v0
	global_store_short v[80:81], v16, off offset:128
	v_cvt_pk_bf16_f32 v16, v32, v32
	v_mul_f32_e32 v0, v1, v0
	global_store_short v[80:81], v16, off offset:192
	v_cvt_pk_bf16_f32 v16, v17, v17
	global_store_short v[82:83], v16, off offset:128
	v_cvt_pk_bf16_f32 v0, v0, v0
	global_store_short v[82:83], v0, off offset:192
	v_rcp_f32_e32 v0, v66
	s_nop 0
	v_mul_f32_e32 v1, v50, v0
	v_cvt_pk_bf16_f32 v1, v1, v1
	v_mul_f32_e32 v16, v34, v0
	v_mul_f32_e32 v17, v18, v0
	global_store_short v[80:81], v1, off offset:256
	v_cvt_pk_bf16_f32 v1, v16, v16
	v_mul_f32_e32 v0, v2, v0
	global_store_short v[80:81], v1, off offset:320
	v_cvt_pk_bf16_f32 v1, v17, v17
	global_store_short v[82:83], v1, off offset:256
	v_cvt_pk_bf16_f32 v0, v0, v0
	global_store_short v[82:83], v0, off offset:320
	v_rcp_f32_e32 v0, v67
	s_nop 0
	v_mul_f32_e32 v1, v51, v0
	v_cvt_pk_bf16_f32 v1, v1, v1
	v_mul_f32_e32 v2, v35, v0
	v_mul_f32_e32 v16, v19, v0
	global_store_short v[80:81], v1, off offset:384
	v_cvt_pk_bf16_f32 v1, v2, v2
	v_mul_f32_e32 v0, v3, v0
	global_store_short v[80:81], v1, off offset:448
	v_cvt_pk_bf16_f32 v1, v16, v16
	global_store_short v[82:83], v1, off offset:384
; #define SBAR() __builtin_amdgcn_sched_barrier(0)
; __device__ __forceinline__ unsigned short f2bf(float x) { return (unsigned short)(cvtpk(x, x) & 0xffffu); }
; __device__ __forceinline__ void attn_body8(const bf16* __restrict__ Qb, const unsigned char* __restrict__ Kg, const unsigned char* __restrict__ Vg, ...
;     ...
;   unsigned short* Ow = reinterpret_cast<unsigned short*>(Ob) + (wid * QBLK + 4 * hi) * 64 + r32;
; #pragma unroll
;   for (int r = 0; r < 16; ++r) { const int orow = (r & 3) + 8 * (r >> 2); const float rl = __builtin_amdgcn_rcpf(lacc[r]);
; #pragma unroll
;     for (int d0 = 0; d0 < 4; ++d0) Ow[orow * 64 + (d0 >> 1) * 16384 + (d0 & 1) * 32] = f2bf(o[d0][r] * rl);
;     SBAR(); }
	v_cvt_pk_bf16_f32 v0, v0, v0
	global_store_short v[82:83], v0, off offset:448
	v_rcp_f32_e32 v0, v68
	s_nop 0
	v_mul_f32_e32 v1, v52, v0
	v_cvt_pk_bf16_f32 v1, v1, v1
	v_mul_f32_e32 v2, v36, v0
	v_mul_f32_e32 v3, v20, v0
	global_store_short v[80:81], v1, off offset:1024
	v_cvt_pk_bf16_f32 v1, v2, v2
	v_mul_f32_e32 v0, v4, v0
	global_store_short v[80:81], v1, off offset:1088
	v_cvt_pk_bf16_f32 v1, v3, v3
	global_store_short v[82:83], v1, off offset:1024
	v_cvt_pk_bf16_f32 v0, v0, v0
	global_store_short v[82:83], v0, off offset:1088
	v_rcp_f32_e32 v0, v69
	s_nop 0
	v_mul_f32_e32 v1, v53, v0
	v_cvt_pk_bf16_f32 v1, v1, v1
	v_mul_f32_e32 v2, v37, v0
	v_mul_f32_e32 v3, v21, v0
	global_store_short v[80:81], v1, off offset:1152
	v_cvt_pk_bf16_f32 v1, v2, v2
	v_mul_f32_e32 v0, v5, v0
	global_store_short v[80:81], v1, off offset:1216
	v_cvt_pk_bf16_f32 v1, v3, v3
	global_store_short v[82:83], v1, off offset:1152
	v_cvt_pk_bf16_f32 v0, v0, v0
	global_store_short v[82:83], v0, off offset:1216
	v_rcp_f32_e32 v0, v70
	s_nop 0
	v_mul_f32_e32 v1, v54, v0
	v_cvt_pk_bf16_f32 v1, v1, v1
	v_mul_f32_e32 v2, v38, v0
	v_mul_f32_e32 v3, v22, v0
	global_store_short v[80:81], v1, off offset:1280
	v_cvt_pk_bf16_f32 v1, v2, v2
	v_mul_f32_e32 v0, v6, v0
	global_store_short v[80:81], v1, off offset:1344
	v_cvt_pk_bf16_f32 v1, v3, v3
	global_store_short v[82:83], v1, off offset:1280
	v_cvt_pk_bf16_f32 v0, v0, v0
	global_store_short v[82:83], v0, off offset:1344
	v_rcp_f32_e32 v0, v71
	s_nop 0
	v_mul_f32_e32 v1, v55, v0
	v_cvt_pk_bf16_f32 v1, v1, v1
	v_mul_f32_e32 v2, v39, v0
	v_mul_f32_e32 v3, v23, v0
	global_store_short v[80:81], v1, off offset:1408
	v_cvt_pk_bf16_f32 v1, v2, v2
	v_mul_f32_e32 v0, v7, v0
	global_store_short v[80:81], v1, off offset:1472
	v_cvt_pk_bf16_f32 v1, v3, v3
	global_store_short v[82:83], v1, off offset:1408
	v_cvt_pk_bf16_f32 v0, v0, v0
	global_store_short v[82:83], v0, off offset:1472
	v_rcp_f32_e32 v0, v72
	s_nop 0
	v_mul_f32_e32 v1, v56, v0
	v_cvt_pk_bf16_f32 v1, v1, v1
	v_mul_f32_e32 v2, v40, v0
	v_mul_f32_e32 v3, v24, v0
	global_store_short v[80:81], v1, off offset:2048
	v_cvt_pk_bf16_f32 v1, v2, v2
	v_mul_f32_e32 v0, v8, v0
	global_store_short v[80:81], v1, off offset:2112
	v_cvt_pk_bf16_f32 v1, v3, v3
	global_store_short v[82:83], v1, off offset:2048
	v_cvt_pk_bf16_f32 v0, v0, v0
	global_store_short v[82:83], v0, off offset:2112
	v_rcp_f32_e32 v0, v73
	s_nop 0
	v_mul_f32_e32 v1, v57, v0
	v_cvt_pk_bf16_f32 v1, v1, v1
	v_mul_f32_e32 v2, v41, v0
	v_mul_f32_e32 v3, v25, v0
	global_store_short v[80:81], v1, off offset:2176
	v_cvt_pk_bf16_f32 v1, v2, v2
	v_mul_f32_e32 v0, v9, v0
	global_store_short v[80:81], v1, off offset:2240
	v_cvt_pk_bf16_f32 v1, v3, v3
	global_store_short v[82:83], v1, off offset:2176
	v_cvt_pk_bf16_f32 v0, v0, v0
	global_store_short v[82:83], v0, off offset:2240
	v_rcp_f32_e32 v0, v74
	s_nop 0
	v_mul_f32_e32 v1, v58, v0
	v_cvt_pk_bf16_f32 v1, v1, v1
	v_mul_f32_e32 v2, v42, v0
	v_mul_f32_e32 v3, v26, v0
	global_store_short v[80:81], v1, off offset:2304
	v_cvt_pk_bf16_f32 v1, v2, v2
	v_mul_f32_e32 v0, v10, v0
	global_store_short v[80:81], v1, off offset:2368
	v_cvt_pk_bf16_f32 v1, v3, v3
	global_store_short v[82:83], v1, off offset:2304
	v_cvt_pk_bf16_f32 v0, v0, v0
	global_store_short v[82:83], v0, off offset:2368
	v_rcp_f32_e32 v0, v75
	s_nop 0
	v_mul_f32_e32 v1, v59, v0
	v_cvt_pk_bf16_f32 v1, v1, v1
	v_mul_f32_e32 v2, v43, v0
	v_mul_f32_e32 v3, v27, v0
	global_store_short v[80:81], v1, off offset:2432
	v_cvt_pk_bf16_f32 v1, v2, v2
	v_mul_f32_e32 v0, v11, v0
	global_store_short v[80:81], v1, off offset:2496
	v_cvt_pk_bf16_f32 v1, v3, v3
	global_store_short v[82:83], v1, off offset:2432
	v_cvt_pk_bf16_f32 v0, v0, v0
	global_store_short v[82:83], v0, off offset:2496
	v_rcp_f32_e32 v0, v76
	s_nop 0
	v_mul_f32_e32 v1, v60, v0
	v_cvt_pk_bf16_f32 v1, v1, v1
	v_mul_f32_e32 v2, v44, v0
	v_mul_f32_e32 v3, v28, v0
	global_store_short v[80:81], v1, off offset:3072
	v_cvt_pk_bf16_f32 v1, v2, v2
	v_mul_f32_e32 v0, v12, v0
	global_store_short v[80:81], v1, off offset:3136
	v_cvt_pk_bf16_f32 v1, v3, v3
	global_store_short v[82:83], v1, off offset:3072
	v_cvt_pk_bf16_f32 v0, v0, v0
	global_store_short v[82:83], v0, off offset:3136
	v_rcp_f32_e32 v0, v77
	s_nop 0
	v_mul_f32_e32 v1, v61, v0
	v_cvt_pk_bf16_f32 v1, v1, v1
	v_mul_f32_e32 v2, v45, v0
	v_mul_f32_e32 v3, v29, v0
	global_store_short v[80:81], v1, off offset:3200
	v_cvt_pk_bf16_f32 v1, v2, v2
	v_mul_f32_e32 v0, v13, v0
	global_store_short v[80:81], v1, off offset:3264
	v_cvt_pk_bf16_f32 v1, v3, v3
	global_store_short v[82:83], v1, off offset:3200
	v_cvt_pk_bf16_f32 v0, v0, v0
	global_store_short v[82:83], v0, off offset:3264
	v_rcp_f32_e32 v0, v78
	s_nop 0
	v_mul_f32_e32 v1, v62, v0
	v_cvt_pk_bf16_f32 v1, v1, v1
	v_mul_f32_e32 v2, v46, v0
	v_mul_f32_e32 v3, v30, v0
	global_store_short v[80:81], v1, off offset:3328
	v_cvt_pk_bf16_f32 v1, v2, v2
	v_mul_f32_e32 v0, v14, v0
	global_store_short v[80:81], v1, off offset:3392
	v_cvt_pk_bf16_f32 v1, v3, v3
	global_store_short v[82:83], v1, off offset:3328
	v_cvt_pk_bf16_f32 v0, v0, v0
	global_store_short v[82:83], v0, off offset:3392
	v_rcp_f32_e32 v0, v79
	s_nop 0
	v_mul_f32_e32 v1, v63, v0
	v_cvt_pk_bf16_f32 v1, v1, v1
	v_mul_f32_e32 v2, v47, v0
	v_mul_f32_e32 v3, v31, v0
	global_store_short v[80:81], v1, off offset:3456
	v_cvt_pk_bf16_f32 v1, v2, v2
	v_mul_f32_e32 v0, v15, v0
	global_store_short v[80:81], v1, off offset:3520
	v_cvt_pk_bf16_f32 v1, v3, v3
	global_store_short v[82:83], v1, off offset:3456
	v_cvt_pk_bf16_f32 v0, v0, v0
	global_store_short v[82:83], v0, off offset:3520
	s_add_i32 s63, s63, s88
	s_cmpk_lt_i32 s63, 0xc00
	s_waitcnt vmcnt(63) expcnt(7) lgkmcnt(15)
	s_barrier
	s_cbranch_scc0 .LBB0_933

; #define SBAR() __builtin_amdgcn_sched_barrier(0)
; #define RESC(a) do { if (__any((a) < 1.f)) { if (hi == 0) al_l[r32] = (a); asm volatile("s_waitcnt lgkmcnt(0)" ::: "memory"); \
;     _Pragma("unroll") for (int d = 0; d < 4; ++d) _Pragma("unroll") for (int r = 0; r < 16; ++r) o[d][r] *= al_l[crow(r, hi)]; } } while (0)
; #define RESC(a) do { if (__any((a) < 1.f)) { if (hi == 0) al_l[r32] = (a); asm volatile("s_waitcnt lgkmcnt(0)" ::: "memory"); \
;     _Pragma("unroll") for (int r = 0; r < 16; ++r) { const float a_ = al_l[crow(r, hi)]; lacc[r] *= a_; _Pragma("unroll") for (int d = 0; d < 4; ++d) o[d][r] *= a_; } } } while (0)
; __device__ __forceinline__ void partialSM8(f32x16& p0, f32x16& p1, float& m_reg, float& mn, float& alpha) {
;   float pmax = p0[0];
; #pragma unroll
;   for (int r = 1; r < 16; ++r) pmax = fmaxf(pmax, p0[r]);
; #pragma unroll
;   for (int r = 0; r < 16; ++r) pmax = fmaxf(pmax, p1[r]);
;   { auto rr = __builtin_amdgcn_permlane32_swap(__float_as_uint(pmax), __float_as_uint(pmax), false, false);
;     pmax = fmaxf(__uint_as_float(rr[0]), __uint_as_float(rr[1])); }
;   if (__builtin_expect(__all(pmax - m_reg <= THR8 * 8.f * 1.4426950408889634f), 1)) { mn = m_reg; alpha = 1.f; }
;   else { mn = fmaxf(m_reg, pmax); alpha = __builtin_amdgcn_exp2f((m_reg - mn) * 0.125f); m_reg = mn; }
;   const float mn8 = (P8SHIFT + 7.f - 0.0436f) * 8.f + 0.5f - mn;
; #pragma unroll
;   for (int r = 0; r < 16; ++r) p0[r] += mn8;
; #pragma unroll
;   for (int r = 0; r < 16; ++r) p1[r] += mn8;
; }
; __device__ __forceinline__ void attn_body8(const bf16* __restrict__ Qb, const unsigned char* __restrict__ Kg, const unsigned char* __restrict__ Vg, ...
;     ...
;     SBAR(); qkt8(pB0, pB1, K_lds + k4 * SHM_K8, qf, r32, hi);
;     finishSM8(pA0, pA1, pf); SBAR();
;     pv8(o, lacc, V_lds + VM1() * SHM_V8, pf, r32, hi); partialSM8(pB0, pB1, m_reg, mnB, alB);
;     RESC(alB);
.LBB0_912:
	s_mul_i32 s2, s22, 0x3400
	v_add_u32_e32 v113, s2, v214
	ds_read_b128 v[80:83], v113 offset:51200
	ds_read_b128 v[84:87], v113 offset:51216
	s_waitcnt lgkmcnt(0)
	v_mfma_scale_f32_32x32x64_f8f6f4 v[96:111], v[80:87], v[120:127], 0, v193, v193 op_sel_hi:[0,0,0]
	ds_read_b128 v[80:83], v113 offset:57856
	ds_read_b128 v[84:87], v113 offset:57872
	ds_read_b128 v[218:221], v113 offset:51264
	ds_read_b128 v[222:225], v113 offset:51280
	s_waitcnt lgkmcnt(2)
	v_mfma_scale_f32_32x32x64_f8f6f4 v[80:95], v[80:87], v[120:127], 0, v193, v193 op_sel_hi:[0,0,0]
	s_waitcnt lgkmcnt(0)
	v_mfma_scale_f32_32x32x64_f8f6f4 v[96:111], v[218:225], v[128:135], v[96:111], v193, v193 op_sel_hi:[0,0,0]
	ds_read_b128 v[218:221], v113 offset:57920
	ds_read_b128 v[222:225], v113 offset:57936
	ds_read_b128 v[226:229], v113 offset:51328
	ds_read_b128 v[230:233], v113 offset:51344
	ds_read_b128 v[234:237], v113 offset:57984
	ds_read_b128 v[238:241], v113 offset:58000
	v_cvt_pk_u8_f32 v113, v184, 0, 0
	v_cvt_pk_u8_f32 v113, v185, 1, v113
	v_cvt_pk_u8_f32 v113, v182, 2, v113
	s_waitcnt lgkmcnt(4)
	v_mfma_scale_f32_32x32x64_f8f6f4 v[80:95], v[218:225], v[128:135], v[80:95], v193, v193 op_sel_hi:[0,0,0]
	v_cvt_pk_u8_f32 v218, v183, 3, v113
	v_cvt_pk_u8_f32 v113, v198, 0, 0
	v_cvt_pk_u8_f32 v113, v199, 1, v113
	v_cvt_pk_u8_f32 v113, v196, 2, v113
	v_cvt_pk_u8_f32 v222, v197, 3, v113
	v_cvt_pk_u8_f32 v113, v178, 0, 0
	v_cvt_pk_u8_f32 v113, v179, 1, v113
	v_cvt_pk_u8_f32 v113, v174, 2, v113
	v_cvt_pk_u8_f32 v219, v175, 3, v113
	v_cvt_pk_u8_f32 v113, v194, 0, 0
	v_cvt_pk_u8_f32 v113, v195, 1, v113
	v_cvt_pk_u8_f32 v113, v190, 2, v113
	v_cvt_pk_u8_f32 v223, v191, 3, v113
	v_cvt_pk_u8_f32 v113, v172, 0, 0
	v_cvt_pk_u8_f32 v113, v173, 1, v113
	s_waitcnt lgkmcnt(2)
	v_mfma_scale_f32_32x32x64_f8f6f4 v[96:111], v[226:233], v[136:143], v[96:111], v193, v193 op_sel_hi:[0,0,0]
	v_cvt_pk_u8_f32 v113, v118, 2, v113
	v_cvt_pk_u8_f32 v220, v119, 3, v113
	v_cvt_pk_u8_f32 v113, v188, 0, 0
	v_cvt_pk_u8_f32 v113, v189, 1, v113
	v_cvt_pk_u8_f32 v113, v186, 2, v113
	v_cvt_pk_u8_f32 v224, v187, 3, v113
	v_cvt_pk_u8_f32 v113, v116, 0, 0
	v_cvt_pk_u8_f32 v113, v117, 1, v113
	v_cvt_pk_u8_f32 v113, v114, 2, v113
	v_cvt_pk_u8_f32 v221, v115, 3, v113
	v_cvt_pk_u8_f32 v113, v180, 0, 0
	v_cvt_pk_u8_f32 v113, v181, 1, v113
	v_cvt_pk_u8_f32 v113, v176, 2, v113
	v_cvt_pk_u8_f32 v225, v177, 3, v113
	s_waitcnt lgkmcnt(0)
	v_mfma_scale_f32_32x32x64_f8f6f4 v[80:95], v[234:241], v[136:143], v[80:95], v193, v193 op_sel_hi:[0,0,0]
	s_mul_i32 s2, s21, 0x2800
	s_addk_i32 s2, 0xd800
	s_cmp_lg_u32 s21, 0
	s_cselect_b32 s2, s2, 0xa000
	v_add_u32_e32 v113, s2, v217
	ds_read_b128 v[172:175], v113
	ds_read_b128 v[176:179], v113 offset:16
	v_max_f32_e32 v188, v97, v97
	v_max_f32_e32 v189, v96, v96
	v_max_f32_e32 v188, v189, v188
	v_max3_f32 v188, v188, v98, v99
	s_waitcnt lgkmcnt(0)
	v_mfma_scale_f32_32x32x64_f8f6f4 v[48:63], v[218:225], v[172:179], v[48:63], v193, v193 op_sel_hi:[0,0,0]
	ds_read_b128 v[172:175], v113 offset:2560
	ds_read_b128 v[176:179], v113 offset:2576
	s_waitcnt lgkmcnt(0)
	v_mfma_scale_f32_32x32x64_f8f6f4 v[32:47], v[218:225], v[172:179], v[32:47], v193, v193 op_sel_hi:[0,0,0]
	ds_read_b128 v[172:175], v113 offset:5120
	ds_read_b128 v[176:179], v113 offset:5136
	ds_read_b128 v[180:183], v113 offset:7680
	ds_read_b128 v[184:187], v113 offset:7696
	s_waitcnt lgkmcnt(2)
	v_mfma_scale_f32_32x32x64_f8f6f4 v[16:31], v[218:225], v[172:179], v[16:31], v193, v193 op_sel_hi:[0,0,0]
	v_max3_f32 v172, v188, v100, v101
	v_max3_f32 v172, v172, v102, v103
	v_max3_f32 v172, v172, v104, v105
	v_max3_f32 v172, v172, v106, v107
	v_max3_f32 v172, v172, v108, v109
	v_max3_f32 v172, v172, v110, v111
	v_max3_f32 v172, v172, v80, v81
	v_max3_f32 v172, v172, v82, v83
	v_max3_f32 v172, v172, v84, v85
	v_max3_f32 v172, v172, v86, v87
	v_max3_f32 v172, v172, v88, v89
	v_max3_f32 v172, v172, v90, v91
	v_max3_f32 v172, v172, v92, v93
	v_max3_f32 v172, v172, v94, v95
	v_mov_b32_e32 v173, v172
	s_waitcnt lgkmcnt(0)
	v_mfma_scale_f32_32x32x64_f8f6f4 v[0:15], v[218:225], v[180:187], v[0:15], v193, v193 op_sel_hi:[0,0,0]
	v_permlane32_swap_b32_e32 v172, v173
	v_max_f32_e32 v172, v172, v173
	v_sub_f32_e32 v173, v172, v216
	v_cmp_ge_f32_e32 vcc, s61, v173
	s_cmp_eq_u64 vcc, exec
	s_cselect_b64 s[10:11], -1, 0
	v_mfma_scale_f32_16x16x128_f8f6f4 v[64:67], v[218:225], v[244:251], v[64:67], v193, v193 op_sel_hi:[0,0,0]
	s_cbranch_scc1 .LBB0_916
	v_max_f32_e32 v172, v216, v172
	v_sub_f32_e32 v174, v216, v172
	v_mul_f32_e32 v174, 0x3e000000, v174
	v_exp_f32_e32 v174, v174
	s_nop 0
	v_mov_b32_e32 v173, v174
	v_cmp_gt_f32_e32 vcc, 1.0, v173
	s_cbranch_vccz .LBB0_916
	s_and_saveexec_b64 s[16:17], s[8:9]
	ds_write_b32 v215, v173 offset:128
	s_or_b64 exec, exec, s[16:17]
	s_waitcnt lgkmcnt(0)
	v_add_u32_e32 v113, v159, v213
	ds_read_b128 v[114:117], v113 offset:224
	ds_read_b128 v[174:177], v113 offset:192
	ds_read_b128 v[178:181], v113 offset:160
	ds_read_b128 v[182:185], v113 offset:128
	s_waitcnt lgkmcnt(3)
	v_pk_mul_f32 v[60:61], v[60:61], v[114:115]
	s_waitcnt lgkmcnt(2)
	v_pk_mul_f32 v[56:57], v[56:57], v[174:175]
	s_waitcnt lgkmcnt(1)
	v_pk_mul_f32 v[52:53], v[52:53], v[178:179]
	v_pk_mul_f32 v[62:63], v[62:63], v[116:117]
	v_pk_mul_f32 v[58:59], v[58:59], v[176:177]
	v_pk_mul_f32 v[54:55], v[54:55], v[180:181]
	s_waitcnt lgkmcnt(0)
	v_pk_mul_f32 v[50:51], v[50:51], v[184:185]
	v_pk_mul_f32 v[48:49], v[48:49], v[182:183]
	v_pk_mul_f32 v[44:45], v[44:45], v[114:115]
	v_pk_mul_f32 v[40:41], v[40:41], v[174:175]
	v_pk_mul_f32 v[36:37], v[36:37], v[178:179]
	v_pk_mul_f32 v[46:47], v[46:47], v[116:117]
	v_pk_mul_f32 v[42:43], v[42:43], v[176:177]
	v_pk_mul_f32 v[38:39], v[38:39], v[180:181]
	v_pk_mul_f32 v[34:35], v[34:35], v[184:185]
	v_pk_mul_f32 v[32:33], v[32:33], v[182:183]
	v_pk_mul_f32 v[28:29], v[28:29], v[114:115]
	v_pk_mul_f32 v[24:25], v[24:25], v[174:175]
	v_pk_mul_f32 v[20:21], v[20:21], v[178:179]
	v_pk_mul_f32 v[30:31], v[30:31], v[116:117]
	v_pk_mul_f32 v[26:27], v[26:27], v[176:177]
	v_pk_mul_f32 v[22:23], v[22:23], v[180:181]
	v_pk_mul_f32 v[18:19], v[18:19], v[184:185]
	v_pk_mul_f32 v[16:17], v[16:17], v[182:183]
	v_pk_mul_f32 v[12:13], v[12:13], v[114:115]
	v_pk_mul_f32 v[8:9], v[8:9], v[174:175]
	v_pk_mul_f32 v[4:5], v[4:5], v[178:179]
	v_pk_mul_f32 v[14:15], v[14:15], v[116:117]
	v_pk_mul_f32 v[10:11], v[10:11], v[176:177]
	v_pk_mul_f32 v[6:7], v[6:7], v[180:181]
	v_pk_mul_f32 v[2:3], v[2:3], v[184:185]
	v_pk_mul_f32 v[0:1], v[0:1], v[182:183]
	ds_read_b128 v[114:117], v242 offset:128
	s_waitcnt lgkmcnt(0)
	v_pk_mul_f32 v[64:65], v[64:65], v[114:115]
	v_pk_mul_f32 v[66:67], v[66:67], v[116:117]

; #define SBAR() __builtin_amdgcn_sched_barrier(0)
; #define RESC(a) do { if (__any((a) < 1.f)) { if (hi == 0) al_l[r32] = (a); asm volatile("s_waitcnt lgkmcnt(0)" ::: "memory"); \
;     _Pragma("unroll") for (int d = 0; d < 4; ++d) _Pragma("unroll") for (int r = 0; r < 16; ++r) o[d][r] *= al_l[crow(r, hi)]; } } while (0)
; #define RESC(a) do { if (__any((a) < 1.f)) { if (hi == 0) al_l[r32] = (a); asm volatile("s_waitcnt lgkmcnt(0)" ::: "memory"); \
;     _Pragma("unroll") for (int r = 0; r < 16; ++r) { const float a_ = al_l[crow(r, hi)]; lacc[r] *= a_; _Pragma("unroll") for (int d = 0; d < 4; ++d) o[d][r] *= a_; } } } while (0)
; __device__ __forceinline__ void partialSM8(f32x16& p0, f32x16& p1, float& m_reg, float& mn, float& alpha) {
;   float pmax = p0[0];
; #pragma unroll
;   for (int r = 1; r < 16; ++r) pmax = fmaxf(pmax, p0[r]);
; #pragma unroll
;   for (int r = 0; r < 16; ++r) pmax = fmaxf(pmax, p1[r]);
;   { auto rr = __builtin_amdgcn_permlane32_swap(__float_as_uint(pmax), __float_as_uint(pmax), false, false);
;     pmax = fmaxf(__uint_as_float(rr[0]), __uint_as_float(rr[1])); }
;   if (__builtin_expect(__all(pmax - m_reg <= THR8 * 8.f * 1.4426950408889634f), 1)) { mn = m_reg; alpha = 1.f; }
;   else { mn = fmaxf(m_reg, pmax); alpha = __builtin_amdgcn_exp2f((m_reg - mn) * 0.125f); m_reg = mn; }
;   const float mn8 = (P8SHIFT + 7.f - 0.0436f) * 8.f + 0.5f - mn;
; #pragma unroll
;   for (int r = 0; r < 16; ++r) p0[r] += mn8;
; #pragma unroll
;   for (int r = 0; r < 16; ++r) p1[r] += mn8;
; }
; __device__ __forceinline__ void attn_body8(const bf16* __restrict__ Qb, const unsigned char* __restrict__ Kg, const unsigned char* __restrict__ Vg, ...
;     ...
;     SBAR(); qkt8(pA0, pA1, K_lds + k4 * SHM_K8, qf, r32, hi);
;     finishSM8(pB0, pB1, pf); SBAR();
;     pv8(o, lacc, V_lds + VM1() * SHM_V8, pf, r32, hi); partialSM8(pA0, pA1, m_reg, mnA, alA);
;     RESC(alA);
.LBB0_924:
	v_cndmask_b32_e64 v168, v172, v216, s[10:11]
	v_sub_f32_e32 v113, 0x42c04d6a, v168
	s_add_i32 s2, s22, 1
	v_add_f32_e32 v169, v102, v113
	s_and_b32 s2, s2, 3
	v_add_f32_e32 v114, v96, v113
	v_add_f32_e32 v115, v97, v113
	v_add_f32_e32 v116, v98, v113
	v_add_f32_e32 v117, v99, v113
	v_add_f32_e32 v118, v100, v113
	v_add_f32_e32 v119, v101, v113
	v_add_f32_e32 v186, v103, v113
	v_add_f32_e32 v187, v104, v113
	v_add_f32_e32 v188, v105, v113
	v_add_f32_e32 v189, v106, v113
	v_add_f32_e32 v190, v107, v113
	v_add_f32_e32 v191, v108, v113
	v_add_f32_e32 v194, v109, v113
	v_add_f32_e32 v195, v110, v113
	v_add_f32_e32 v196, v111, v113
	v_add_f32_e32 v197, v80, v113
	v_add_f32_e32 v198, v81, v113
	v_add_f32_e32 v199, v82, v113
	v_add_f32_e32 v202, v83, v113
	v_add_f32_e32 v203, v84, v113
	v_add_f32_e32 v204, v85, v113
	v_add_f32_e32 v205, v86, v113
	v_add_f32_e32 v207, v87, v113
	v_add_f32_e32 v216, v88, v113
	v_add_f32_e32 v226, v89, v113
	v_add_f32_e32 v227, v90, v113
	v_add_f32_e32 v228, v91, v113
	v_add_f32_e32 v229, v92, v113
	v_add_f32_e32 v230, v93, v113
	v_add_f32_e32 v231, v94, v113
	v_add_f32_e32 v113, v95, v113
	s_mulk_i32 s2, 0x3400
	v_add_u32_e32 v222, s2, v214
	ds_read_b128 v[80:83], v222 offset:51200
	ds_read_b128 v[84:87], v222 offset:51216
	v_cvt_pk_u8_f32 v114, v114, 0, 0
	v_cvt_pk_u8_f32 v114, v115, 1, v114
	v_cvt_pk_u8_f32 v114, v116, 2, v114
	s_waitcnt lgkmcnt(0)
	v_mfma_scale_f32_32x32x64_f8f6f4 v[96:111], v[80:87], v[120:127], 0, v193, v193 op_sel_hi:[0,0,0]
	ds_read_b128 v[80:83], v222 offset:57856
	ds_read_b128 v[84:87], v222 offset:57872
	ds_read_b128 v[170:173], v222 offset:51264
	ds_read_b128 v[174:177], v222 offset:51280
	s_waitcnt lgkmcnt(2)
	v_mfma_scale_f32_32x32x64_f8f6f4 v[80:95], v[80:87], v[120:127], 0, v193, v193 op_sel_hi:[0,0,0]
	s_waitcnt lgkmcnt(0)
	v_mfma_scale_f32_32x32x64_f8f6f4 v[96:111], v[170:177], v[128:135], v[96:111], v193, v193 op_sel_hi:[0,0,0]
	ds_read_b128 v[170:173], v222 offset:57920
	ds_read_b128 v[174:177], v222 offset:57936
	ds_read_b128 v[178:181], v222 offset:51328
	ds_read_b128 v[182:185], v222 offset:51344
	ds_read_b128 v[218:221], v222 offset:57984
	ds_read_b128 v[222:225], v222 offset:58000
	s_waitcnt lgkmcnt(4)
	v_mfma_scale_f32_32x32x64_f8f6f4 v[80:95], v[170:177], v[128:135], v[80:95], v193, v193 op_sel_hi:[0,0,0]
	v_cvt_pk_u8_f32 v172, v117, 3, v114
	v_cvt_pk_u8_f32 v114, v197, 0, 0
	v_cvt_pk_u8_f32 v114, v198, 1, v114
	v_cvt_pk_u8_f32 v114, v199, 2, v114
	v_cvt_pk_u8_f32 v176, v202, 3, v114
	v_cvt_pk_u8_f32 v114, v118, 0, 0
	v_cvt_pk_u8_f32 v114, v119, 1, v114
	v_cvt_pk_u8_f32 v114, v169, 2, v114
	v_cvt_pk_u8_f32 v173, v186, 3, v114
	v_cvt_pk_u8_f32 v114, v203, 0, 0
	v_cvt_pk_u8_f32 v114, v204, 1, v114
	v_cvt_pk_u8_f32 v114, v205, 2, v114
	v_cvt_pk_u8_f32 v177, v207, 3, v114
	v_cvt_pk_u8_f32 v114, v187, 0, 0
	v_cvt_pk_u8_f32 v114, v188, 1, v114
	s_waitcnt lgkmcnt(2)
	v_mfma_scale_f32_32x32x64_f8f6f4 v[96:111], v[178:185], v[136:143], v[96:111], v193, v193 op_sel_hi:[0,0,0]
	v_cvt_pk_u8_f32 v114, v189, 2, v114
	v_cvt_pk_u8_f32 v174, v190, 3, v114
	v_cvt_pk_u8_f32 v114, v216, 0, 0
	v_cvt_pk_u8_f32 v114, v226, 1, v114
	v_cvt_pk_u8_f32 v114, v227, 2, v114
	v_cvt_pk_u8_f32 v178, v228, 3, v114
	v_cvt_pk_u8_f32 v114, v191, 0, 0
	v_cvt_pk_u8_f32 v114, v194, 1, v114
	v_cvt_pk_u8_f32 v114, v195, 2, v114
	v_cvt_pk_u8_f32 v175, v196, 3, v114
	v_cvt_pk_u8_f32 v114, v229, 0, 0
	v_cvt_pk_u8_f32 v114, v230, 1, v114
	v_cvt_pk_u8_f32 v114, v231, 2, v114
	v_cvt_pk_u8_f32 v179, v113, 3, v114
	s_waitcnt lgkmcnt(0)
	v_mfma_scale_f32_32x32x64_f8f6f4 v[80:95], v[218:225], v[136:143], v[80:95], v193, v193 op_sel_hi:[0,0,0]
	s_mul_i32 s2, s16, 0x2800
	s_addk_i32 s2, 0xd800
	s_cmp_lg_u32 s16, 0
	s_cselect_b32 s2, s2, 0xa000
	v_add_u32_e32 v113, s2, v217
	ds_read_b128 v[180:183], v113
	ds_read_b128 v[184:187], v113 offset:16
	v_max_f32_e32 v169, v97, v97
	v_max_f32_e32 v170, v96, v96
	v_max_f32_e32 v169, v170, v169
	v_max3_f32 v169, v169, v98, v99
	v_max3_f32 v169, v169, v100, v101
	s_waitcnt lgkmcnt(0)
	v_mfma_scale_f32_32x32x64_f8f6f4 v[48:63], v[172:179], v[180:187], v[48:63], v193, v193 op_sel_hi:[0,0,0]
	ds_read_b128 v[180:183], v113 offset:2560
	ds_read_b128 v[184:187], v113 offset:2576
	v_max3_f32 v169, v169, v102, v103
	v_max3_f32 v169, v169, v104, v105
	v_max3_f32 v169, v169, v106, v107
	v_max3_f32 v169, v169, v108, v109
	v_max3_f32 v169, v169, v110, v111
	v_max3_f32 v169, v169, v80, v81
	v_max3_f32 v169, v169, v82, v83
	v_max3_f32 v169, v169, v84, v85
	v_max3_f32 v169, v169, v86, v87
	s_waitcnt lgkmcnt(0)
	v_mfma_scale_f32_32x32x64_f8f6f4 v[32:47], v[172:179], v[180:187], v[32:47], v193, v193 op_sel_hi:[0,0,0]
	ds_read_b128 v[180:183], v113 offset:5120
	ds_read_b128 v[184:187], v113 offset:5136
	ds_read_b128 v[218:221], v113 offset:7680
	ds_read_b128 v[222:225], v113 offset:7696
	v_max3_f32 v169, v169, v88, v89
	v_max3_f32 v169, v169, v90, v91
	v_max3_f32 v169, v169, v92, v93
	v_max3_f32 v169, v169, v94, v95
	v_mov_b32_e32 v170, v169
	s_nop 1
	v_permlane32_swap_b32_e32 v169, v170
	v_max_f32_e32 v169, v169, v170
	v_sub_f32_e32 v170, v169, v168
	s_waitcnt lgkmcnt(2)
	v_mfma_scale_f32_32x32x64_f8f6f4 v[16:31], v[172:179], v[180:187], v[16:31], v193, v193 op_sel_hi:[0,0,0]
	v_cmp_ge_f32_e32 vcc, s61, v170
	s_cmp_eq_u64 vcc, exec
	s_cselect_b64 s[10:11], -1, 0
	s_waitcnt lgkmcnt(0)
	v_mfma_scale_f32_32x32x64_f8f6f4 v[0:15], v[172:179], v[218:225], v[0:15], v193, v193 op_sel_hi:[0,0,0]
	v_mfma_scale_f32_16x16x128_f8f6f4 v[64:67], v[172:179], v[244:251], v[64:67], v193, v193 op_sel_hi:[0,0,0]
	s_cbranch_scc1 .LBB0_928
; __device__ __forceinline__ void partialSM8(f32x16& p0, f32x16& p1, float& m_reg, float& mn, float& alpha) {
;     ...
;   if (__builtin_expect(__all(pmax - m_reg <= THR8 * 8.f * 1.4426950408889634f), 1)) { mn = m_reg; alpha = 1.f; }
;   else { mn = fmaxf(m_reg, pmax); alpha = __builtin_amdgcn_exp2f((m_reg - mn) * 0.125f); m_reg = mn; }
	v_max_f32_e32 v169, v168, v169
	v_sub_f32_e32 v171, v168, v169
	v_mul_f32_e32 v171, 0x3e000000, v171
	v_exp_f32_e32 v171, v171
	s_nop 0
	v_mov_b32_e32 v170, v171
	v_cmp_gt_f32_e32 vcc, 1.0, v170
	s_cbranch_vccz .LBB0_928
	s_and_saveexec_b64 s[14:15], s[8:9]
	ds_write_b32 v215, v170 offset:128
	s_or_b64 exec, exec, s[14:15]
	s_waitcnt lgkmcnt(0)
	v_add_u32_e32 v113, v159, v213
	ds_read_b128 v[114:117], v113 offset:224
	ds_read_b128 v[170:173], v113 offset:192
	ds_read_b128 v[174:177], v113 offset:160
	ds_read_b128 v[178:181], v113 offset:128
	s_waitcnt lgkmcnt(3)
	v_pk_mul_f32 v[60:61], v[60:61], v[114:115]
	s_waitcnt lgkmcnt(2)
	v_pk_mul_f32 v[56:57], v[56:57], v[170:171]
	s_waitcnt lgkmcnt(1)
	v_pk_mul_f32 v[52:53], v[52:53], v[174:175]
	v_pk_mul_f32 v[62:63], v[62:63], v[116:117]
	v_pk_mul_f32 v[58:59], v[58:59], v[172:173]
	v_pk_mul_f32 v[54:55], v[54:55], v[176:177]
	s_waitcnt lgkmcnt(0)
	v_pk_mul_f32 v[50:51], v[50:51], v[180:181]
	v_pk_mul_f32 v[48:49], v[48:49], v[178:179]
	v_pk_mul_f32 v[44:45], v[44:45], v[114:115]
	v_pk_mul_f32 v[40:41], v[40:41], v[170:171]
	v_pk_mul_f32 v[36:37], v[36:37], v[174:175]
	v_pk_mul_f32 v[46:47], v[46:47], v[116:117]
	v_pk_mul_f32 v[42:43], v[42:43], v[172:173]
	v_pk_mul_f32 v[38:39], v[38:39], v[176:177]
	v_pk_mul_f32 v[34:35], v[34:35], v[180:181]
	v_pk_mul_f32 v[32:33], v[32:33], v[178:179]
	v_pk_mul_f32 v[28:29], v[28:29], v[114:115]
	v_pk_mul_f32 v[24:25], v[24:25], v[170:171]
	v_pk_mul_f32 v[20:21], v[20:21], v[174:175]
	v_pk_mul_f32 v[30:31], v[30:31], v[116:117]
	v_pk_mul_f32 v[26:27], v[26:27], v[172:173]
	v_pk_mul_f32 v[22:23], v[22:23], v[176:177]
	v_pk_mul_f32 v[18:19], v[18:19], v[180:181]
	v_pk_mul_f32 v[16:17], v[16:17], v[178:179]
	v_pk_mul_f32 v[12:13], v[12:13], v[114:115]
	v_pk_mul_f32 v[8:9], v[8:9], v[170:171]
	v_pk_mul_f32 v[4:5], v[4:5], v[174:175]
	v_pk_mul_f32 v[14:15], v[14:15], v[116:117]
	v_pk_mul_f32 v[10:11], v[10:11], v[172:173]
	v_pk_mul_f32 v[6:7], v[6:7], v[176:177]
	v_pk_mul_f32 v[2:3], v[2:3], v[180:181]
	v_pk_mul_f32 v[0:1], v[0:1], v[178:179]
	ds_read_b128 v[114:117], v242 offset:128
	s_waitcnt lgkmcnt(0)
	v_pk_mul_f32 v[64:65], v[64:65], v[114:115]
	v_pk_mul_f32 v[66:67], v[66:67], v[116:117]

; #define SBAR() __builtin_amdgcn_sched_barrier(0)
; #define RESC(a) do { if (__any((a) < 1.f)) { if (hi == 0) al_l[r32] = (a); asm volatile("s_waitcnt lgkmcnt(0)" ::: "memory"); \
;     _Pragma("unroll") for (int d = 0; d < 4; ++d) _Pragma("unroll") for (int r = 0; r < 16; ++r) o[d][r] *= al_l[crow(r, hi)]; } } while (0)
; #define RESC(a) do { if (__any((a) < 1.f)) { if (hi == 0) al_l[r32] = (a); asm volatile("s_waitcnt lgkmcnt(0)" ::: "memory"); \
;     _Pragma("unroll") for (int r = 0; r < 16; ++r) { const float a_ = al_l[crow(r, hi)]; lacc[r] *= a_; _Pragma("unroll") for (int d = 0; d < 4; ++d) o[d][r] *= a_; } } } while (0)
; __device__ __forceinline__ void attn_body8(const bf16* __restrict__ Qb, const unsigned char* __restrict__ Kg, const unsigned char* __restrict__ Vg, ...
;     ...
;   __syncthreads();
;   SBAR(); qkt8(pB0, pB1, K_lds + k4 * SHM_K8, qf, r32, hi);
;   finishSM8(pA0, pA1, pf); SBAR();
;   pv8(o, lacc, V_lds + VM1() * SHM_V8, pf, r32, hi); partialSM8(pB0, pB1, m_reg, mnB, alB);
;   RESC(alB);
;   finishSM8(pB0, pB1, pf); SBAR();
;   pv8(o, lacc, V_lds + v5 * SHM_V8, pf, r32, hi);
.LBB0_930:
	s_waitcnt vmcnt(0)
	v_mul_u32_u24_e32 v146, 0x50, v209
	s_barrier
	v_add3_u32 v113, s20, v212, v144
	ds_read_b128 v[80:83], v113 offset:51200
	ds_read_b128 v[84:87], v113 offset:51216
	ds_read_b128 v[96:99], v113 offset:57856
	ds_read_b128 v[100:103], v113 offset:57872
	s_waitcnt lgkmcnt(2)
	v_mfma_scale_f32_32x32x64_f8f6f4 v[80:95], v[80:87], v[120:127], 0, v193, v193 op_sel_hi:[0,0,0]
	s_waitcnt lgkmcnt(0)
	v_mfma_scale_f32_32x32x64_f8f6f4 v[96:111], v[96:103], v[120:127], 0, v193, v193 op_sel_hi:[0,0,0]
	ds_read_b128 v[120:123], v113 offset:51264
	ds_read_b128 v[124:127], v113 offset:51280
	s_waitcnt lgkmcnt(0)
	v_mfma_scale_f32_32x32x64_f8f6f4 v[80:95], v[120:127], v[128:135], v[80:95], v193, v193 op_sel_hi:[0,0,0]
	ds_read_b128 v[120:123], v113 offset:57920
	ds_read_b128 v[124:127], v113 offset:57936
	ds_read_b128 v[148:151], v113 offset:51328
	ds_read_b128 v[152:155], v113 offset:51344
	ds_read_b128 v[160:163], v113 offset:57984
	ds_read_b128 v[164:167], v113 offset:58000
	v_cvt_pk_u8_f32 v113, v184, 0, 0
	v_cvt_pk_u8_f32 v113, v185, 1, v113
	v_cvt_pk_u8_f32 v113, v182, 2, v113
	s_waitcnt lgkmcnt(4)
	v_mfma_scale_f32_32x32x64_f8f6f4 v[96:111], v[120:127], v[128:135], v[96:111], v193, v193 op_sel_hi:[0,0,0]
	v_cvt_pk_u8_f32 v122, v183, 3, v113
	v_cvt_pk_u8_f32 v113, v198, 0, 0
	v_cvt_pk_u8_f32 v113, v199, 1, v113
	v_cvt_pk_u8_f32 v113, v196, 2, v113
	v_cvt_pk_u8_f32 v126, v197, 3, v113
	v_cvt_pk_u8_f32 v113, v178, 0, 0
	v_cvt_pk_u8_f32 v113, v179, 1, v113
	v_cvt_pk_u8_f32 v113, v174, 2, v113
	v_cvt_pk_u8_f32 v123, v175, 3, v113
	v_cvt_pk_u8_f32 v113, v194, 0, 0
	v_cvt_pk_u8_f32 v113, v195, 1, v113
	v_cvt_pk_u8_f32 v113, v190, 2, v113
	v_cvt_pk_u8_f32 v127, v191, 3, v113
	v_cvt_pk_u8_f32 v113, v172, 0, 0
	v_cvt_pk_u8_f32 v113, v173, 1, v113
	s_waitcnt lgkmcnt(2)
	v_mfma_scale_f32_32x32x64_f8f6f4 v[80:95], v[148:155], v[136:143], v[80:95], v193, v193 op_sel_hi:[0,0,0]
	v_cvt_pk_u8_f32 v113, v118, 2, v113
	v_cvt_pk_u8_f32 v124, v119, 3, v113
	v_cvt_pk_u8_f32 v113, v188, 0, 0
	v_cvt_pk_u8_f32 v113, v189, 1, v113
	v_cvt_pk_u8_f32 v113, v186, 2, v113
	v_cvt_pk_u8_f32 v128, v187, 3, v113
	v_cvt_pk_u8_f32 v113, v116, 0, 0
	v_cvt_pk_u8_f32 v113, v117, 1, v113
	v_cvt_pk_u8_f32 v113, v114, 2, v113
	v_cvt_pk_u8_f32 v125, v115, 3, v113
	v_cvt_pk_u8_f32 v113, v180, 0, 0
	v_cvt_pk_u8_f32 v113, v181, 1, v113
	v_cvt_pk_u8_f32 v113, v176, 2, v113
	v_cvt_pk_u8_f32 v129, v177, 3, v113
	s_waitcnt lgkmcnt(0)
	v_mfma_scale_f32_32x32x64_f8f6f4 v[96:111], v[160:167], v[136:143], v[96:111], v193, v193 op_sel_hi:[0,0,0]
	s_mul_i32 s12, s21, 0x2800
	s_add_i32 s2, s12, 0xffffd800
	s_cmp_lg_u32 s21, 0
	s_cselect_b32 s2, s2, 0xa000
	s_add_i32 s2, s2, 0
	v_add3_u32 v113, s2, v146, v144
	ds_read_b128 v[114:117], v113
	ds_read_b128 v[118:121], v113 offset:16
	s_waitcnt lgkmcnt(0)
	v_mfma_scale_f32_32x32x64_f8f6f4 v[48:63], v[122:129], v[114:121], v[48:63], v193, v193 op_sel_hi:[0,0,0]
	ds_read_b128 v[114:117], v113 offset:2560
	ds_read_b128 v[118:121], v113 offset:2576
	ds_read_b128 v[130:133], v113 offset:5120
	ds_read_b128 v[134:137], v113 offset:5136
	ds_read_b128 v[148:151], v113 offset:7680
	ds_read_b128 v[152:155], v113 offset:7696
	s_waitcnt lgkmcnt(4)
	v_mfma_scale_f32_32x32x64_f8f6f4 v[32:47], v[122:129], v[114:121], v[32:47], v193, v193 op_sel_hi:[0,0,0]
	v_max_f32_e32 v120, v81, v81
	v_max_f32_e32 v121, v80, v80
	v_max_f32_e32 v120, v121, v120
	v_max3_f32 v120, v120, v82, v83
	v_max3_f32 v120, v120, v84, v85
	v_max3_f32 v120, v120, v86, v87
	v_max3_f32 v120, v120, v88, v89
	v_max3_f32 v120, v120, v90, v91
	v_max3_f32 v120, v120, v92, v93
	v_max3_f32 v120, v120, v94, v95
	v_max3_f32 v120, v120, v96, v97
	v_max3_f32 v120, v120, v98, v99
	v_max3_f32 v120, v120, v100, v101
	v_max3_f32 v120, v120, v102, v103
	v_max3_f32 v120, v120, v104, v105
	s_waitcnt lgkmcnt(2)
	v_mfma_scale_f32_32x32x64_f8f6f4 v[16:31], v[122:129], v[130:137], v[16:31], v193, v193 op_sel_hi:[0,0,0]
	v_max3_f32 v120, v120, v106, v107
	v_max3_f32 v120, v120, v108, v109
	v_max3_f32 v120, v120, v110, v111
	v_mov_b32_e32 v121, v120
	s_nop 1
	v_permlane32_swap_b32_e32 v120, v121
	v_max_f32_e32 v121, v121, v121
	v_max_f32_e32 v120, v120, v120
	v_max_f32_e32 v120, v120, v121
	v_max_f32_e32 v130, v216, v216
	v_sub_f32_e32 v121, v120, v216
	v_max_f32_e32 v120, v130, v120
	v_sub_f32_e32 v130, v216, v120
	v_mul_f32_e32 v130, 0x3e000000, v130
	v_exp_f32_e32 v130, v130
	s_waitcnt lgkmcnt(0)
	v_mfma_scale_f32_32x32x64_f8f6f4 v[0:15], v[122:129], v[148:155], v[0:15], v193, v193 op_sel_hi:[0,0,0]
	v_cmp_ge_f32_e32 vcc, s61, v121
	s_cmp_eq_u64 vcc, exec
	s_cselect_b64 s[6:7], -1, 0
	v_cndmask_b32_e64 v121, v130, 1.0, s[6:7]
	v_cmp_gt_f32_e32 vcc, 1.0, v121
	v_mfma_scale_f32_16x16x128_f8f6f4 v[64:67], v[122:129], v[244:251], v[64:67], v193, v193 op_sel_hi:[0,0,0]
	s_cbranch_vccz .LBB0_890
	s_and_saveexec_b64 s[10:11], s[8:9]
	s_cbranch_execz .LBB0_889
	ds_write_b32 v215, v121 offset:128
	s_branch .LBB0_889
